# phase-3 loop QK^T: 8 K-fragment ds_reads per half issued up front into private quads with counted lgkmcnt (lever 8 LDS/MFMA interleave)
# speedup vs baseline: 1.0084x; 1.0036x over previous
; #define MFMA16(a, b, c) __builtin_amdgcn_mfma_f32_16x16x32_f16((a), (b), (c), 0, 0, 0)
; DI void qk_tile2(f32x4 (&sa)[4], f32x4 (&sb)[4], const char* sK, const bf16x8 (&qa)[2], const bf16x8 (&qb)[2], int lr, int g) {
; #pragma unroll
;   for (int kt = 0; kt < 4; ++kt) {
;     const bf16x8 k0 = *(const bf16x8*)(sK + (kt * 16 + lr) * 128 + ((g ^ ((lr >> 1) & 7)) << 4)), k1 = *(const bf16x8*)(sK + (kt * 16 + lr) * 128 + (((4 + g) ^ ((lr >> 1) & 7)) << 4));
;     sa[kt] = MFMA16(k0, qa[0], ((f32x4){0.f, 0.f, 0.f, 0.f})); sb[kt] = MFMA16(k0, qb[0], ((f32x4){0.f, 0.f, 0.f, 0.f}));
;     sa[kt] = MFMA16(k1, qa[1], sa[kt]); sb[kt] = MFMA16(k1, qb[1], sb[kt]);
;   }
; }
; DI float softmax_step(f32x4 (&st)[4], float& m, float& lsum) {
;   float mx = fmaxf(fmaxf(fmaxf(st[0][0], st[0][1]), fmaxf(st[0][2], st[0][3])), fmaxf(fmaxf(st[1][0], st[1][1]), fmaxf(st[1][2], st[1][3])));
;   mx = fmaxf(mx, fmaxf(fmaxf(fmaxf(st[2][0], st[2][1]), fmaxf(st[2][2], st[2][3])), fmaxf(fmaxf(st[3][0], st[3][1]), fmaxf(st[3][2], st[3][3]))));
;   mx = fmaxf(mx, __shfl_xor(mx, 16)); mx = fmaxf(mx, __shfl_xor(mx, 32));
.LBB0_1079:
	v_readlane_b32 s16, v254, 55
	s_add_i32 s1, s15, -2
	v_readlane_b32 s18, v254, 57
	v_readlane_b32 s19, v254, 58
	v_cmp_le_i32_e32 vcc, s1, v107
	v_readlane_b32 s17, v254, 56
	v_lshl_add_u64 v[122:123], s[18:19], 0, v[112:113]
	s_and_saveexec_b64 s[12:13], vcc
	s_cbranch_execz .LBB0_1081
	v_add_co_u32_e32 v80, vcc, 0x1b900000, v122
	s_mov_b32 s16, 0xff800000
	s_nop 0
	v_addc_co_u32_e32 v81, vcc, 0, v123, vcc
	global_load_dwordx2 v[126:127], v[80:81], off
	v_add_co_u32_e32 v80, vcc, 0x1b902000, v122
	s_waitcnt vmcnt(0)
	v_lshrrev_b32_e32 v147, v132, v126
	v_addc_co_u32_e32 v81, vcc, 0, v123, vcc
	global_load_dwordx2 v[128:129], v[80:81], off
	ds_read_b128 v[200:203], v139
	ds_read_b128 v[204:207], v140
	ds_read_b128 v[208:211], v139 offset:2048
	ds_read_b128 v[212:215], v140 offset:2048
	ds_read_b128 v[220:223], v139 offset:4096
	ds_read_b128 v[224:227], v140 offset:4096
	ds_read_b128 v[228:231], v139 offset:6144
	ds_read_b128 v[232:235], v140 offset:6144
	s_waitcnt lgkmcnt(7)
	v_mfma_f32_16x16x32_f16 v[88:91], v[200:203], v[0:3], 0
	v_and_b32_e32 v130, 1, v147
	v_cmp_eq_u32_e32 vcc, 1, v130
	v_bfe_i32 v141, v147, 1, 1
	v_mfma_f32_16x16x32_f16 v[80:83], v[200:203], v[4:7], 0
	v_lshrrev_b32_e32 v126, v138, v126
	s_waitcnt lgkmcnt(6)
	v_mfma_f32_16x16x32_f16 v[142:145], v[204:207], v[8:11], v[88:91]
	v_mfma_f32_16x16x32_f16 v[154:157], v[204:207], v[12:15], v[80:83]
	s_nop 3
	s_waitcnt lgkmcnt(5)
	v_mfma_f32_16x16x32_f16 v[88:91], v[208:211], v[0:3], 0
	v_mfma_f32_16x16x32_f16 v[80:83], v[208:211], v[4:7], 0
	s_waitcnt lgkmcnt(4)
	v_mfma_f32_16x16x32_f16 v[100:103], v[212:215], v[8:11], v[88:91]
	v_mfma_f32_16x16x32_f16 v[96:99], v[212:215], v[12:15], v[80:83]
	s_nop 4
	s_waitcnt lgkmcnt(3)
	v_mfma_f32_16x16x32_f16 v[84:87], v[220:223], v[0:3], 0
	v_mfma_f32_16x16x32_f16 v[80:83], v[220:223], v[4:7], 0
	s_waitcnt lgkmcnt(2)
	v_mfma_f32_16x16x32_f16 v[84:87], v[224:227], v[8:11], v[84:87]
	v_mfma_f32_16x16x32_f16 v[80:83], v[224:227], v[12:15], v[80:83]
	s_waitcnt lgkmcnt(1)
	v_mfma_f32_16x16x32_f16 v[158:161], v[228:231], v[0:3], 0
	v_mfma_f32_16x16x32_f16 v[162:165], v[228:231], v[4:7], 0
	s_waitcnt lgkmcnt(0)
	v_mfma_f32_16x16x32_f16 v[88:91], v[232:235], v[8:11], v[158:161]
	s_nop 4
	v_cndmask_b32_e32 v159, v187, v142, vcc
	v_bfe_i32 v142, v147, 2, 1
	v_mfma_f32_16x16x32_f16 v[92:95], v[232:235], v[12:15], v[162:165]
	s_waitcnt vmcnt(0)
	v_lshrrev_b32_e32 v158, v132, v128
	v_and_b32_e32 v130, 1, v158
	v_cmp_eq_u32_e32 vcc, 1, v130
	v_lshrrev_b32_e32 v128, v138, v128
	s_nop 0
	v_cndmask_b32_e32 v130, v187, v154, vcc
	v_bfi_b32 v154, v141, v143, v187
	v_and_b32_e32 v141, 2, v158
	v_cmp_ne_u32_e32 vcc, 0, v141
	v_bfe_i32 v143, v147, 3, 1
	v_bfe_i32 v147, v126, 0, 1
	v_cndmask_b32_e32 v141, v187, v155, vcc
	v_bfi_b32 v144, v142, v144, v187
	v_and_b32_e32 v142, 4, v158
	v_cmp_ne_u32_e32 vcc, 0, v142
	s_nop 1
	v_cndmask_b32_e32 v142, v187, v156, vcc
	v_bfi_b32 v145, v143, v145, v187
	v_and_b32_e32 v143, 8, v158
	v_cmp_ne_u32_e32 vcc, 0, v143
	s_nop 1
	v_cndmask_b32_e32 v143, v187, v157, vcc
	v_bfi_b32 v100, v147, v100, v187
	v_and_b32_e32 v147, 1, v128
	v_cmp_eq_u32_e32 vcc, 1, v147
	s_nop 1
	v_cndmask_b32_e32 v147, v187, v96, vcc
	v_and_b32_e32 v96, 2, v126
	v_cmp_ne_u32_e32 vcc, 0, v96
	s_nop 1
	v_cndmask_b32_e32 v96, v187, v101, vcc
	v_bfe_i32 v101, v128, 1, 1
	v_bfi_b32 v97, v101, v97, v187
	v_and_b32_e32 v101, 4, v126
	v_cmp_ne_u32_e32 vcc, 0, v101
	s_nop 1
	v_cndmask_b32_e32 v101, v187, v102, vcc
	v_bfe_i32 v102, v128, 2, 1
	v_bfi_b32 v98, v102, v98, v187
	v_and_b32_e32 v102, 8, v126
	v_lshrrev_b32_e32 v126, v132, v129
	v_cmp_ne_u32_e32 vcc, 0, v102
	s_nop 1
	v_cndmask_b32_e32 v102, v187, v103, vcc
	v_and_b32_e32 v103, 8, v128
	v_cmp_ne_u32_e32 vcc, 0, v103
	s_nop 1
	v_cndmask_b32_e32 v103, v187, v99, vcc
	v_lshrrev_b32_e32 v99, v132, v127
	v_bfe_i32 v128, v99, 0, 1
	v_bfi_b32 v84, v128, v84, v187
	v_and_b32_e32 v128, 1, v126
	v_cmp_eq_u32_e32 vcc, 1, v128
	s_nop 1
	v_cndmask_b32_e32 v128, v187, v80, vcc
	v_and_b32_e32 v80, 2, v99
	v_cmp_ne_u32_e32 vcc, 0, v80
	s_nop 1
	v_cndmask_b32_e32 v80, v187, v85, vcc
	v_bfe_i32 v85, v126, 1, 1
	v_bfi_b32 v81, v85, v81, v187
	v_and_b32_e32 v85, 4, v99
	v_cmp_ne_u32_e32 vcc, 0, v85
	s_nop 1
	v_cndmask_b32_e32 v85, v187, v86, vcc
	v_bfe_i32 v86, v126, 2, 1
	v_bfi_b32 v155, v86, v82, v187
	v_bfe_i32 v86, v126, 3, 1
	v_and_b32_e32 v82, 8, v99
	v_cmp_ne_u32_e32 vcc, 0, v82
	s_nop 1
	v_cndmask_b32_e32 v82, v187, v87, vcc
	v_bfi_b32 v83, v86, v83, v187
	v_lshrrev_b32_e32 v86, v138, v127
	v_lshrrev_b32_e32 v87, v138, v129
	v_bfe_i32 v99, v86, 0, 1
	v_bfi_b32 v88, v99, v88, v187
	v_bfe_i32 v99, v87, 0, 1
	v_bfi_b32 v126, v99, v92, v187
	v_bfe_i32 v92, v86, 1, 1
	v_bfi_b32 v89, v92, v89, v187
	v_bfe_i32 v92, v87, 1, 1
	v_bfi_b32 v127, v92, v93, v187
	v_bfe_i32 v92, v86, 2, 1
	v_bfe_i32 v86, v86, 3, 1
	v_bfi_b32 v93, v92, v90, v187
	v_bfe_i32 v90, v87, 2, 1
	v_bfi_b32 v129, v90, v94, v187
	v_bfi_b32 v91, v86, v91, v187
	v_bfe_i32 v86, v87, 3, 1
	v_bfi_b32 v156, v86, v95, v187
	v_max_f32_e32 v86, v144, v145
	v_max_f32_e32 v87, v101, v102
	v_max_f32_e32 v90, v84, v80
	v_max_f32_e32 v92, v85, v82
	v_max_f32_e32 v94, v93, v91
	v_max3_f32 v94, v88, v89, v94
	v_max3_f32 v86, v159, v154, v86
	v_max3_f32 v87, v100, v96, v87
	v_max3_f32 v90, v90, v92, v94
	v_max3_f32 v86, v86, v87, v90
	v_mov_b32_e32 v87, v86
	s_waitcnt lgkmcnt(0)
	s_nop 1
	v_permlane16_swap_b32_e32 v86, v87
	v_max_f32_e32 v86, v86, v87
	v_mov_b32_e32 v87, v86
	s_waitcnt lgkmcnt(0)
; DI float softmax_step(f32x4 (&st)[4], float& m, float& lsum) {
;   float mx = fmaxf(fmaxf(fmaxf(st[0][0], st[0][1]), fmaxf(st[0][2], st[0][3])), fmaxf(fmaxf(st[1][0], st[1][1]), fmaxf(st[1][2], st[1][3])));
;   mx = fmaxf(mx, fmaxf(fmaxf(fmaxf(st[2][0], st[2][1]), fmaxf(st[2][2], st[2][3])), fmaxf(fmaxf(st[3][0], st[3][1]), fmaxf(st[3][2], st[3][3]))));
;   mx = fmaxf(mx, __shfl_xor(mx, 16)); mx = fmaxf(mx, __shfl_xor(mx, 32));
;   const float mn = fmaxf(m, mx);
;   const float mu = mn == -INFINITY ? 0.f : mn;
;   const float alpha = __builtin_amdgcn_exp2f(m - mu);
;   float ps = 0.f;
; #pragma unroll
;   for (int kt = 0; kt < 4; ++kt)
; #pragma unroll
;     for (int j = 0; j < 4; ++j) { const float p = __builtin_amdgcn_exp2f(st[kt][j] - mu); st[kt][j] = p; ps += p; }
;   lsum = lsum * alpha + ps; m = mn;
;   return alpha;
; }
	s_nop 1
	v_permlane32_swap_b32_e32 v86, v87
	v_max3_f32 v99, v131, v86, v87
	v_cmp_neq_f32_e32 vcc, s16, v99
	s_nop 1
	v_cndmask_b32_e32 v87, 0, v99, vcc
	v_sub_f32_e32 v86, v159, v87
	v_exp_f32_e32 v162, v86
	v_sub_f32_e32 v86, v154, v87
	v_exp_f32_e32 v164, v86
	v_sub_f32_e32 v86, v144, v87
	v_exp_f32_e32 v166, v86
	v_sub_f32_e32 v86, v145, v87
	v_sub_f32_e32 v80, v80, v87
	v_exp_f32_e32 v168, v86
	v_sub_f32_e32 v86, v100, v87
	v_exp_f32_e32 v94, v80
	v_sub_f32_e32 v80, v85, v87
	v_exp_f32_e32 v170, v86
	v_sub_f32_e32 v86, v96, v87
	v_exp_f32_e32 v92, v80
	v_sub_f32_e32 v80, v82, v87
	v_exp_f32_e32 v190, v86
	v_sub_f32_e32 v86, v101, v87
	v_exp_f32_e32 v90, v80
	v_sub_f32_e32 v80, v88, v87
	v_exp_f32_e32 v192, v86
	v_sub_f32_e32 v86, v102, v87
	v_exp_f32_e32 v88, v80
	v_sub_f32_e32 v80, v89, v87
	v_exp_f32_e32 v194, v86
	v_sub_f32_e32 v84, v84, v87
	v_exp_f32_e32 v86, v80
	v_sub_f32_e32 v80, v93, v87
	v_exp_f32_e32 v96, v84
	v_exp_f32_e32 v82, v80
	v_sub_f32_e32 v80, v91, v87
	v_sub_f32_e32 v84, v131, v87
	v_max_f32_e32 v85, v142, v143
	v_max_f32_e32 v87, v98, v103
	v_max_f32_e32 v89, v128, v81
	v_max_f32_e32 v91, v155, v83
	v_max_f32_e32 v93, v129, v156
	v_max3_f32 v93, v126, v127, v93
	v_max3_f32 v85, v130, v141, v85
	v_max3_f32 v87, v147, v97, v87
	v_max3_f32 v89, v89, v91, v93
	v_max3_f32 v85, v85, v87, v89
	v_mov_b32_e32 v87, v85
	v_exp_f32_e32 v84, v84
	v_exp_f32_e32 v80, v80
	v_mov_b32_e32 v131, v99
	s_waitcnt lgkmcnt(0)
	s_nop 1
	v_permlane16_swap_b32_e32 v85, v87
	v_max_f32_e32 v85, v85, v87
	v_mov_b32_e32 v87, v85
	s_waitcnt lgkmcnt(0)
	s_nop 1
	v_permlane32_swap_b32_e32 v85, v87
	v_max3_f32 v102, v146, v85, v87
	v_cmp_neq_f32_e32 vcc, s16, v102
	s_nop 1
	v_cndmask_b32_e32 v85, 0, v102, vcc
	v_sub_f32_e32 v87, v130, v85
	v_exp_f32_e32 v163, v87
	v_sub_f32_e32 v87, v141, v85
	v_exp_f32_e32 v165, v87
	v_sub_f32_e32 v87, v142, v85
	v_exp_f32_e32 v167, v87
	v_sub_f32_e32 v87, v143, v85
	v_exp_f32_e32 v169, v87
	v_sub_f32_e32 v87, v147, v85
	v_sub_f32_e32 v81, v81, v85
	v_exp_f32_e32 v171, v87
	v_sub_f32_e32 v87, v97, v85
	v_exp_f32_e32 v95, v81
	v_sub_f32_e32 v81, v155, v85
	v_exp_f32_e32 v191, v87
	v_sub_f32_e32 v87, v98, v85
	v_exp_f32_e32 v93, v81
	v_sub_f32_e32 v81, v83, v85
	v_exp_f32_e32 v193, v87
	v_sub_f32_e32 v87, v103, v85
	v_exp_f32_e32 v91, v81
	v_sub_f32_e32 v81, v126, v85
	v_exp_f32_e32 v195, v87
	v_sub_f32_e32 v87, v128, v85
	v_exp_f32_e32 v89, v81
	v_sub_f32_e32 v81, v127, v85
	v_exp_f32_e32 v97, v87
	v_exp_f32_e32 v87, v81
	v_sub_f32_e32 v81, v129, v85
	v_exp_f32_e32 v83, v81
	v_sub_f32_e32 v81, v156, v85
	v_sub_f32_e32 v85, v146, v85
	v_exp_f32_e32 v98, v85
	v_pk_mul_f32 v[156:157], v[70:71], v[84:85] op_sel_hi:[1,0]
	v_pk_mul_f32 v[154:155], v[68:69], v[84:85] op_sel_hi:[1,0]
	v_pk_mul_f32 v[128:129], v[62:63], v[84:85] op_sel_hi:[1,0]
	v_pk_mul_f32 v[142:143], v[56:57], v[98:99] op_sel_hi:[1,0]
	v_pk_mul_f32 v[70:71], v[50:51], v[98:99] op_sel_hi:[1,0]
	v_pk_mul_f32 v[68:69], v[48:49], v[98:99] op_sel_hi:[1,0]
	v_pk_mul_f32 v[50:51], v[74:75], v[84:85] op_sel_hi:[1,0]
	v_pk_mul_f32 v[48:49], v[72:73], v[84:85] op_sel_hi:[1,0]
	v_pk_add_f32 v[56:57], v[162:163], 0 op_sel_hi:[1,0]
	ds_read_b128 v[72:75], v139 offset:9216
	v_pk_add_f32 v[56:57], v[164:165], v[56:57]
	v_pk_mul_f32 v[126:127], v[60:61], v[84:85] op_sel_hi:[1,0]
	v_pk_add_f32 v[56:57], v[166:167], v[56:57]
	v_pk_mul_f32 v[144:145], v[58:59], v[98:99] op_sel_hi:[1,0]
	v_pk_add_f32 v[56:57], v[168:169], v[56:57]
	v_cvt_pk_f16_f32 v58, v170, v190
	v_pk_add_f32 v[56:57], v[170:171], v[56:57]
	v_cvt_pk_f16_f32 v59, v192, v194
	v_pk_add_f32 v[56:57], v[190:191], v[56:57]
	v_pk_mul_f32 v[160:161], v[66:67], v[98:99] op_sel_hi:[1,0]
	v_pk_add_f32 v[56:57], v[192:193], v[56:57]
	v_pk_mul_f32 v[158:159], v[64:65], v[98:99] op_sel_hi:[1,0]
	v_pk_add_f32 v[56:57], v[194:195], v[56:57]
	v_pk_mul_f32 v[66:67], v[54:55], v[84:85] op_sel_hi:[1,0]
	v_pk_add_f32 v[100:101], v[96:97], v[56:57]
	v_cvt_pk_f16_f32 v56, v162, v164
	v_cvt_pk_f16_f32 v57, v166, v168
	v_pk_mul_f32 v[64:65], v[52:53], v[84:85] op_sel_hi:[1,0]
	v_pk_mul_f32 v[54:55], v[78:79], v[98:99] op_sel_hi:[1,0]
	v_pk_mul_f32 v[52:53], v[76:77], v[98:99] op_sel_hi:[1,0]
	s_waitcnt lgkmcnt(0)
	v_mfma_f32_16x16x32_f16 v[76:79], v[72:75], v[56:59], v[126:129]
	v_cvt_pk_f16_f32 v60, v163, v165
	v_cvt_pk_f16_f32 v61, v167, v169
	v_cvt_pk_f16_f32 v62, v171, v191
	ds_read_b128 v[126:129], v139 offset:11264
	v_cvt_pk_f16_f32 v63, v193, v195
	v_exp_f32_e32 v81, v81
	v_cvt_pk_f16_f32 v190, v96, v94
	v_mfma_f32_16x16x32_f16 v[72:75], v[72:75], v[60:63], v[142:145]
	v_cvt_pk_f16_f32 v191, v92, v90
	v_cvt_pk_f16_f32 v192, v88, v86
	v_cvt_pk_f16_f32 v193, v82, v80
	s_waitcnt lgkmcnt(0)
	v_mfma_f32_16x16x32_f16 v[142:145], v[126:129], v[56:59], v[154:157]
	v_cvt_pk_f16_f32 v194, v97, v95
	v_cvt_pk_f16_f32 v195, v93, v91
	s_nop 0
	ds_read_b128 v[154:157], v139 offset:13312
	v_mfma_f32_16x16x32_f16 v[126:129], v[126:129], v[60:63], v[158:161]
	v_cvt_pk_f16_f32 v196, v89, v87
	v_cvt_pk_f16_f32 v197, v83, v81
	v_pk_add_f32 v[94:95], v[94:95], v[100:101]
	s_waitcnt lgkmcnt(0)
	v_mfma_f32_16x16x32_f16 v[158:161], v[154:157], v[56:59], v[64:67]
	s_nop 2
	ds_read_b128 v[64:67], v139 offset:15360
	v_pk_add_f32 v[92:93], v[92:93], v[94:95]
	v_mov_b32_e32 v85, v98
	s_waitcnt lgkmcnt(0)
	v_mfma_f32_16x16x32_f16 v[162:165], v[64:67], v[56:59], v[48:51]
	s_nop 2
	ds_read_b128 v[48:51], v140 offset:9216
	v_pk_add_f32 v[90:91], v[90:91], v[92:93]
	v_mov_b32_e32 v146, v102
	v_mfma_f32_16x16x32_f16 v[154:157], v[154:157], v[60:63], v[68:71]
	v_add_f32_e64 v88, v88, v90
	v_add_f32_e64 v89, v89, v91
	v_pk_add_f32 v[86:87], v[86:87], v[88:89]
	v_mfma_f32_16x16x32_f16 v[166:169], v[64:67], v[60:63], v[52:55]
	v_add_f32_e64 v82, v82, v86
	v_add_f32_e64 v83, v83, v87
	v_pk_add_f32 v[80:81], v[80:81], v[82:83]
	s_waitcnt lgkmcnt(0)
	v_mfma_f32_16x16x32_f16 v[60:63], v[48:51], v[190:193], v[76:79]
	v_fma_f32 v118, v118, v84, v80
	v_fma_f32 v119, v119, v85, v81
	v_mfma_f32_16x16x32_f16 v[56:59], v[48:51], v[194:197], v[72:75]
	ds_read_b128 v[48:51], v140 offset:11264
	ds_read_b128 v[76:79], v140 offset:15360
	s_waitcnt lgkmcnt(1)
	v_mfma_f32_16x16x32_f16 v[68:71], v[48:51], v[190:193], v[142:145]
	v_mfma_f32_16x16x32_f16 v[64:67], v[48:51], v[194:197], v[126:129]
	ds_read_b128 v[48:51], v140 offset:13312
	s_waitcnt lgkmcnt(0)
	v_mfma_f32_16x16x32_f16 v[52:55], v[48:51], v[190:193], v[158:161]
	v_mfma_f32_16x16x32_f16 v[48:51], v[48:51], v[194:197], v[154:157]
	v_mfma_f32_16x16x32_f16 v[72:75], v[76:79], v[190:193], v[162:165]
	v_mfma_f32_16x16x32_f16 v[76:79], v[76:79], v[194:197], v[166:169]

; #define MFMA16(a, b, c) __builtin_amdgcn_mfma_f32_16x16x32_f16((a), (b), (c), 0, 0, 0)
; DI void qk_tile2(f32x4 (&sa)[4], f32x4 (&sb)[4], const char* sK, const bf16x8 (&qa)[2], const bf16x8 (&qb)[2], int lr, int g) {
; #pragma unroll
;   for (int kt = 0; kt < 4; ++kt) {
;     const bf16x8 k0 = *(const bf16x8*)(sK + (kt * 16 + lr) * 128 + ((g ^ ((lr >> 1) & 7)) << 4)), k1 = *(const bf16x8*)(sK + (kt * 16 + lr) * 128 + (((4 + g) ^ ((lr >> 1) & 7)) << 4));
;     sa[kt] = MFMA16(k0, qa[0], ((f32x4){0.f, 0.f, 0.f, 0.f})); sb[kt] = MFMA16(k0, qb[0], ((f32x4){0.f, 0.f, 0.f, 0.f}));
;     sa[kt] = MFMA16(k1, qa[1], sa[kt]); sb[kt] = MFMA16(k1, qb[1], sb[kt]);
;   }
; }
; DI float softmax_step(f32x4 (&st)[4], float& m, float& lsum) {
;   float mx = fmaxf(fmaxf(fmaxf(st[0][0], st[0][1]), fmaxf(st[0][2], st[0][3])), fmaxf(fmaxf(st[1][0], st[1][1]), fmaxf(st[1][2], st[1][3])));
;   mx = fmaxf(mx, fmaxf(fmaxf(fmaxf(st[2][0], st[2][1]), fmaxf(st[2][2], st[2][3])), fmaxf(fmaxf(st[3][0], st[3][1]), fmaxf(st[3][2], st[3][3]))));
;   mx = fmaxf(mx, __shfl_xor(mx, 16)); mx = fmaxf(mx, __shfl_xor(mx, 32));
.LBB0_1085:
	v_add_co_u32_e32 v80, vcc, 0x1b900000, v122
	s_mov_b32 s1, 0xff800000
	s_nop 0
	v_addc_co_u32_e32 v81, vcc, 0, v123, vcc
	global_load_dwordx2 v[128:129], v[80:81], off offset:8
	v_add_co_u32_e32 v80, vcc, 0x1b902000, v122
	s_nop 1
	v_addc_co_u32_e32 v81, vcc, 0, v123, vcc
	global_load_dwordx2 v[144:145], v[80:81], off offset:8
	ds_read_b128 v[200:203], v139 offset:18432
	ds_read_b128 v[204:207], v140 offset:18432
	ds_read_b128 v[208:211], v139 offset:20480
	ds_read_b128 v[212:215], v140 offset:20480
	ds_read_b128 v[220:223], v139 offset:22528
	ds_read_b128 v[224:227], v140 offset:22528
	ds_read_b128 v[228:231], v139 offset:24576
	ds_read_b128 v[232:235], v140 offset:24576
	s_waitcnt lgkmcnt(7)
	v_mfma_f32_16x16x32_f16 v[88:91], v[200:203], v[0:3], 0
	v_mfma_f32_16x16x32_f16 v[80:83], v[200:203], v[4:7], 0
	s_waitcnt lgkmcnt(6)
	v_mfma_f32_16x16x32_f16 v[88:91], v[204:207], v[8:11], v[88:91]
	v_mfma_f32_16x16x32_f16 v[80:83], v[204:207], v[12:15], v[80:83]
	s_waitcnt lgkmcnt(5)
	v_mfma_f32_16x16x32_f16 v[96:99], v[208:211], v[0:3], 0
	v_mfma_f32_16x16x32_f16 v[84:87], v[208:211], v[4:7], 0
	s_waitcnt lgkmcnt(4)
	v_mfma_f32_16x16x32_f16 v[96:99], v[212:215], v[8:11], v[96:99]
	v_mfma_f32_16x16x32_f16 v[84:87], v[212:215], v[12:15], v[84:87]
	s_waitcnt lgkmcnt(3)
	v_mfma_f32_16x16x32_f16 v[120:123], v[220:223], v[0:3], 0
	v_mfma_f32_16x16x32_f16 v[92:95], v[220:223], v[4:7], 0
	s_waitcnt lgkmcnt(2)
	v_mfma_f32_16x16x32_f16 v[120:123], v[224:227], v[8:11], v[120:123]
	v_mfma_f32_16x16x32_f16 v[92:95], v[224:227], v[12:15], v[92:95]
	s_waitcnt lgkmcnt(1)
	v_mfma_f32_16x16x32_f16 v[154:157], v[228:231], v[0:3], 0
	v_mfma_f32_16x16x32_f16 v[100:103], v[228:231], v[4:7], 0
	s_waitcnt lgkmcnt(0)
	v_mfma_f32_16x16x32_f16 v[154:157], v[232:235], v[8:11], v[154:157]
	v_mfma_f32_16x16x32_f16 v[100:103], v[232:235], v[12:15], v[100:103]
	s_waitcnt vmcnt(1)
	v_lshrrev_b32_e32 v124, v132, v128
	v_bfe_i32 v126, v124, 0, 1
	v_bfi_b32 v88, v126, v88, v187
	s_waitcnt vmcnt(0)
	v_lshrrev_b32_e32 v125, v132, v144
	v_bfe_i32 v126, v125, 0, 1
	v_bfi_b32 v80, v126, v80, v187
	v_bfe_i32 v126, v124, 1, 1
	v_bfi_b32 v89, v126, v89, v187
	v_bfe_i32 v126, v125, 1, 1
	v_bfi_b32 v81, v126, v81, v187
	v_bfe_i32 v126, v124, 2, 1
	v_bfe_i32 v124, v124, 3, 1
	v_bfi_b32 v90, v126, v90, v187
	v_bfe_i32 v126, v125, 2, 1
	v_bfi_b32 v82, v126, v82, v187
	v_bfi_b32 v91, v124, v91, v187
	v_bfe_i32 v124, v125, 3, 1
	v_lshrrev_b32_e32 v125, v138, v144
	v_bfi_b32 v83, v124, v83, v187
	v_lshrrev_b32_e32 v124, v138, v128
	v_bfe_i32 v126, v124, 0, 1
	v_bfi_b32 v96, v126, v96, v187
	v_bfe_i32 v126, v125, 0, 1
	v_bfi_b32 v127, v126, v84, v187
	v_bfe_i32 v84, v124, 1, 1
	v_bfi_b32 v97, v84, v97, v187
	v_bfe_i32 v84, v125, 1, 1
	v_bfi_b32 v147, v84, v85, v187
	v_bfe_i32 v84, v124, 2, 1
	v_bfi_b32 v85, v84, v98, v187
	v_bfe_i32 v84, v125, 2, 1
	v_bfi_b32 v98, v84, v86, v187
	v_bfe_i32 v84, v124, 3, 1
	v_bfi_b32 v99, v84, v99, v187
	v_bfe_i32 v84, v125, 3, 1
	v_lshrrev_b32_e32 v86, v132, v145
	v_bfi_b32 v125, v84, v87, v187
	v_lshrrev_b32_e32 v84, v132, v129
	v_and_b32_e32 v87, 1, v84
	v_cmp_eq_u32_e32 vcc, 1, v87
	s_nop 1
	v_cndmask_b32_e32 v87, v187, v120, vcc
	v_bfe_i32 v120, v86, 0, 1
	v_bfi_b32 v92, v120, v92, v187
	v_and_b32_e32 v120, 2, v84
	v_cmp_ne_u32_e32 vcc, 0, v120
	s_nop 1
	v_cndmask_b32_e32 v120, v187, v121, vcc
	v_bfe_i32 v121, v86, 1, 1
	v_bfi_b32 v93, v121, v93, v187
	v_and_b32_e32 v121, 4, v84
	v_bfe_i32 v84, v84, 3, 1
	v_cmp_ne_u32_e32 vcc, 0, v121
	s_nop 1
	v_cndmask_b32_e32 v121, v187, v122, vcc
	v_bfe_i32 v122, v86, 2, 1
	v_bfi_b32 v94, v122, v94, v187
	v_bfi_b32 v122, v84, v123, v187
	v_bfe_i32 v84, v86, 3, 1
	v_lshrrev_b32_e32 v86, v138, v145
	v_bfi_b32 v95, v84, v95, v187
	v_lshrrev_b32_e32 v84, v138, v129
	v_and_b32_e32 v123, 1, v84
	v_cmp_eq_u32_e32 vcc, 1, v123
	v_bfe_i32 v124, v86, 0, 1
	s_nop 0
	v_cndmask_b32_e32 v123, v187, v154, vcc
	v_bfi_b32 v129, v124, v100, v187
	v_bfe_i32 v124, v86, 1, 1
	v_and_b32_e32 v100, 2, v84
	v_cmp_ne_u32_e32 vcc, 0, v100
	s_nop 1
	v_cndmask_b32_e32 v100, v187, v155, vcc
	v_bfi_b32 v101, v124, v101, v187
	v_bfe_i32 v124, v84, 2, 1
	v_bfe_i32 v84, v84, 3, 1
	v_bfi_b32 v128, v124, v156, v187
	v_bfe_i32 v124, v86, 2, 1
	v_bfi_b32 v102, v124, v102, v187
	v_bfi_b32 v130, v84, v157, v187
	v_bfe_i32 v84, v86, 3, 1
	v_bfi_b32 v103, v84, v103, v187
	v_max_f32_e32 v84, v90, v91
	v_max_f32_e32 v86, v85, v99
	v_max_f32_e32 v124, v87, v120
	v_max_f32_e32 v126, v121, v122
	v_max_f32_e32 v144, v128, v130
	v_max3_f32 v144, v123, v100, v144
	v_max3_f32 v84, v88, v89, v84
	v_max3_f32 v86, v96, v97, v86
	v_max3_f32 v124, v124, v126, v144
	v_max3_f32 v84, v84, v86, v124
	v_mov_b32_e32 v86, v84
	s_waitcnt lgkmcnt(0)
	s_nop 1
	v_permlane16_swap_b32_e32 v84, v86
	v_max_f32_e32 v84, v84, v86
	v_mov_b32_e32 v86, v84
	s_waitcnt lgkmcnt(0)
	s_nop 1
	v_permlane32_swap_b32_e32 v84, v86
	v_max3_f32 v144, v131, v84, v86
	v_cmp_neq_f32_e32 vcc, s1, v144
	s_nop 1
	v_cndmask_b32_e32 v145, 0, v144, vcc
	v_sub_f32_e32 v84, v88, v145
	v_sub_f32_e32 v88, v90, v145
	v_exp_f32_e32 v162, v88
	v_sub_f32_e32 v88, v91, v145
	v_sub_f32_e32 v85, v85, v145
	v_exp_f32_e32 v164, v88
	v_sub_f32_e32 v88, v96, v145
	v_exp_f32_e32 v170, v85
	v_sub_f32_e32 v85, v99, v145
	v_exp_f32_e32 v166, v88
	v_sub_f32_e32 v88, v97, v145
	v_exp_f32_e32 v190, v85
	v_sub_f32_e32 v85, v87, v145
	v_exp_f32_e32 v168, v88
	v_exp_f32_e32 v88, v85
	v_sub_f32_e32 v85, v120, v145
	v_exp_f32_e32 v90, v85
	v_sub_f32_e32 v85, v121, v145
	v_exp_f32_e32 v120, v85
	v_sub_f32_e32 v85, v122, v145
	v_exp_f32_e32 v122, v85
	v_sub_f32_e32 v85, v123, v145
	v_exp_f32_e32 v124, v85
	v_sub_f32_e32 v85, v100, v145
	v_exp_f32_e32 v126, v85
	v_sub_f32_e32 v85, v128, v145
	v_exp_f32_e32 v128, v85
	v_sub_f32_e32 v85, v130, v145
	v_exp_f32_e32 v130, v85
	v_sub_f32_e32 v85, v131, v145
	v_exp_f32_e32 v100, v85
	v_sub_f32_e32 v86, v89, v145
	v_max_f32_e32 v85, v82, v83
	v_max_f32_e32 v87, v98, v125
	v_max_f32_e32 v89, v92, v93
	v_max_f32_e32 v91, v94, v95
	v_max_f32_e32 v96, v102, v103
	v_max3_f32 v96, v129, v101, v96
	v_max3_f32 v85, v80, v81, v85
	v_max3_f32 v87, v127, v147, v87
	v_max3_f32 v89, v89, v91, v96
	v_max3_f32 v85, v85, v87, v89
	v_mov_b32_e32 v87, v85
	v_exp_f32_e32 v84, v84
	v_exp_f32_e32 v86, v86
	v_pk_mul_f32 v[70:71], v[70:71], v[100:101] op_sel_hi:[1,0]
	v_pk_mul_f32 v[68:69], v[68:69], v[100:101] op_sel_hi:[1,0]
	s_waitcnt lgkmcnt(0)
; DI float softmax_step(f32x4 (&st)[4], float& m, float& lsum) {
;   float mx = fmaxf(fmaxf(fmaxf(st[0][0], st[0][1]), fmaxf(st[0][2], st[0][3])), fmaxf(fmaxf(st[1][0], st[1][1]), fmaxf(st[1][2], st[1][3])));
;   mx = fmaxf(mx, fmaxf(fmaxf(fmaxf(st[2][0], st[2][1]), fmaxf(st[2][2], st[2][3])), fmaxf(fmaxf(st[3][0], st[3][1]), fmaxf(st[3][2], st[3][3]))));
;   mx = fmaxf(mx, __shfl_xor(mx, 16)); mx = fmaxf(mx, __shfl_xor(mx, 32));
;   const float mn = fmaxf(m, mx);
;   const float mu = mn == -INFINITY ? 0.f : mn;
;   const float alpha = __builtin_amdgcn_exp2f(m - mu);
;   float ps = 0.f;
; #pragma unroll
;   for (int kt = 0; kt < 4; ++kt)
; #pragma unroll
;     for (int j = 0; j < 4; ++j) { const float p = __builtin_amdgcn_exp2f(st[kt][j] - mu); st[kt][j] = p; ps += p; }
;   lsum = lsum * alpha + ps; m = mn;
;   return alpha;
; }
	s_nop 1
	v_permlane16_swap_b32_e32 v85, v87
	v_max_f32_e32 v85, v85, v87
	v_mov_b32_e32 v87, v85
	v_pk_mul_f32 v[156:157], v[54:55], v[100:101] op_sel_hi:[1,0]
	v_pk_mul_f32 v[154:155], v[52:53], v[100:101] op_sel_hi:[1,0]
	s_waitcnt lgkmcnt(0)
	s_nop 1
	v_permlane32_swap_b32_e32 v85, v87
	v_max3_f32 v145, v146, v85, v87
	v_cmp_neq_f32_e32 vcc, s1, v145
	s_nop 1
	v_cndmask_b32_e32 v96, 0, v145, vcc
	v_sub_f32_e32 v80, v80, v96
	v_exp_f32_e32 v85, v80
	v_sub_f32_e32 v80, v81, v96
	v_exp_f32_e32 v87, v80
	v_sub_f32_e32 v80, v82, v96
	v_exp_f32_e32 v163, v80
	v_sub_f32_e32 v80, v83, v96
	v_exp_f32_e32 v165, v80
	v_sub_f32_e32 v80, v127, v96
	v_exp_f32_e32 v167, v80
	v_sub_f32_e32 v80, v147, v96
	v_exp_f32_e32 v169, v80
	v_sub_f32_e32 v80, v98, v96
	v_exp_f32_e32 v171, v80
	v_sub_f32_e32 v80, v125, v96
	v_exp_f32_e32 v191, v80
	v_sub_f32_e32 v80, v92, v96
	v_exp_f32_e32 v89, v80
	v_sub_f32_e32 v80, v93, v96
	v_exp_f32_e32 v91, v80
	v_sub_f32_e32 v80, v94, v96
	v_exp_f32_e32 v121, v80
	v_sub_f32_e32 v80, v95, v96
	v_exp_f32_e32 v123, v80
	v_sub_f32_e32 v80, v129, v96
	v_exp_f32_e32 v125, v80
	v_sub_f32_e32 v80, v101, v96
	v_exp_f32_e32 v127, v80
	v_sub_f32_e32 v80, v102, v96
	v_exp_f32_e32 v129, v80
	v_sub_f32_e32 v80, v103, v96
	v_exp_f32_e32 v131, v80
	v_sub_f32_e32 v80, v146, v96
	v_exp_f32_e32 v102, v80
	v_pk_mul_f32 v[82:83], v[62:63], v[100:101] op_sel_hi:[1,0]
	v_pk_mul_f32 v[80:81], v[60:61], v[100:101] op_sel_hi:[1,0]
	v_cvt_pk_f16_f32 v60, v84, v86
	v_pk_mul_f32 v[160:161], v[50:51], v[102:103] op_sel_hi:[1,0]
	v_pk_mul_f32 v[158:159], v[48:49], v[102:103] op_sel_hi:[1,0]
	v_pk_mul_f32 v[50:51], v[74:75], v[100:101] op_sel_hi:[1,0]
	v_pk_mul_f32 v[48:49], v[72:73], v[100:101] op_sel_hi:[1,0]
	ds_read_b128 v[72:75], v139 offset:29696
	v_pk_mul_f32 v[92:93], v[56:57], v[102:103] op_sel_hi:[1,0]
	v_pk_add_f32 v[56:57], v[84:85], 0 op_sel_hi:[1,0]
	v_pk_mul_f32 v[98:99], v[66:67], v[102:103] op_sel_hi:[1,0]
	v_pk_add_f32 v[56:57], v[86:87], v[56:57]
	v_pk_mul_f32 v[96:97], v[64:65], v[102:103] op_sel_hi:[1,0]
	v_pk_add_f32 v[56:57], v[162:163], v[56:57]
	v_cvt_pk_f16_f32 v61, v162, v164
	v_pk_add_f32 v[56:57], v[164:165], v[56:57]
	v_cvt_pk_f16_f32 v62, v166, v168
	v_pk_add_f32 v[56:57], v[166:167], v[56:57]
	v_cvt_pk_f16_f32 v63, v170, v190
	v_pk_add_f32 v[56:57], v[168:169], v[56:57]
	v_cvt_pk_f16_f32 v84, v85, v87
	v_pk_add_f32 v[56:57], v[170:171], v[56:57]
	v_cvt_pk_f16_f32 v85, v163, v165
	v_cvt_pk_f16_f32 v86, v167, v169
	v_cvt_pk_f16_f32 v87, v171, v191
	ds_read_b128 v[64:67], v139 offset:27648
	v_pk_add_f32 v[56:57], v[190:191], v[56:57]
	s_waitcnt lgkmcnt(1)
	v_mfma_f32_16x16x32_f16 v[68:71], v[72:75], v[60:63], v[68:71]
	v_add_f32_e64 v56, v88, v56
	v_add_f32_e64 v57, v89, v57
	v_pk_mul_f32 v[94:95], v[58:59], v[102:103] op_sel_hi:[1,0]
	v_pk_add_f32 v[56:57], v[90:91], v[56:57]
	v_mfma_f32_16x16x32_f16 v[72:75], v[72:75], v[84:87], v[96:99]
	v_add_f32_e64 v56, v120, v56
	v_add_f32_e64 v57, v121, v57
	v_pk_mul_f32 v[54:55], v[78:79], v[102:103] op_sel_hi:[1,0]
	v_pk_add_f32 v[56:57], v[122:123], v[56:57]
	ds_read_b128 v[96:99], v139 offset:33792
	v_pk_add_f32 v[56:57], v[124:125], v[56:57]
	v_pk_mul_f32 v[52:53], v[76:77], v[102:103] op_sel_hi:[1,0]
	v_pk_add_f32 v[56:57], v[126:127], v[56:57]
	v_mov_b32_e32 v101, v102
	v_pk_add_f32 v[56:57], v[128:129], v[56:57]
	v_mov_b32_e32 v146, v145
	v_pk_add_f32 v[102:103], v[130:131], v[56:57]
	s_waitcnt lgkmcnt(1)
	v_mfma_f32_16x16x32_f16 v[56:59], v[64:67], v[60:63], v[80:83]
	v_fma_f32 v118, v118, v100, v102
	v_fma_f32 v119, v119, v101, v103
	s_nop 0
	ds_read_b128 v[80:83], v139 offset:31744
	v_mfma_f32_16x16x32_f16 v[64:67], v[64:67], v[84:87], v[92:95]
	s_waitcnt lgkmcnt(1)
	v_mfma_f32_16x16x32_f16 v[92:95], v[96:99], v[60:63], v[48:51]
	s_nop 2
	ds_read_b128 v[48:51], v140 offset:27648
	s_waitcnt lgkmcnt(1)
	v_mfma_f32_16x16x32_f16 v[76:79], v[80:83], v[60:63], v[154:157]
	v_mfma_f32_16x16x32_f16 v[80:83], v[80:83], v[84:87], v[158:161]
	v_mfma_f32_16x16x32_f16 v[84:87], v[96:99], v[84:87], v[52:55]
	v_cvt_pk_f16_f32 v96, v88, v90
	v_cvt_pk_f16_f32 v97, v120, v122
	v_cvt_pk_f16_f32 v98, v124, v126
	v_cvt_pk_f16_f32 v99, v128, v130
	v_cvt_pk_f16_f32 v88, v89, v91
	v_cvt_pk_f16_f32 v89, v121, v123
	v_cvt_pk_f16_f32 v90, v125, v127
	v_cvt_pk_f16_f32 v91, v129, v131
	s_waitcnt lgkmcnt(0)
	v_mfma_f32_16x16x32_f16 v[60:63], v[48:51], v[96:99], v[56:59]
	v_mov_b32_e32 v131, v144
	v_mfma_f32_16x16x32_f16 v[56:59], v[48:51], v[88:91], v[64:67]
	ds_read_b128 v[48:51], v140 offset:29696
	s_waitcnt lgkmcnt(0)
	v_mfma_f32_16x16x32_f16 v[68:71], v[48:51], v[96:99], v[68:71]
	v_mfma_f32_16x16x32_f16 v[64:67], v[48:51], v[88:91], v[72:75]
	ds_read_b128 v[48:51], v140 offset:31744
	s_waitcnt lgkmcnt(0)
	v_mfma_f32_16x16x32_f16 v[52:55], v[48:51], v[96:99], v[76:79]
	s_nop 2
	ds_read_b128 v[76:79], v140 offset:33792
	v_mfma_f32_16x16x32_f16 v[48:51], v[48:51], v[88:91], v[80:83]
	s_waitcnt lgkmcnt(0)
	v_mfma_f32_16x16x32_f16 v[72:75], v[76:79], v[96:99], v[92:95]
	v_mfma_f32_16x16x32_f16 v[76:79], v[76:79], v[88:91], v[84:87]
	s_or_b64 exec, exec, s[12:13]
	s_andn2_b64 vcc, exec, s[10:11]
	s_cbranch_vccnz .LBB0_1076
